# W_in forget-gate tile epilogue (pn 14): dead logf guards removed (1759 -> 1254 instructions on the two active waves)
# speedup vs baseline: 1.0078x; 1.0078x over previous
; __device__ __forceinline__ float logsig_f(float x) { return fminf(x, 0.f) - __logf(1.f + __expf(-fabsf(x))); }
;     __device__ __forceinline__ void operator()(const f32x4 (&acc)[2][2][4][2], const pg8::Unit& u, int wr, int wc, int fr, int fq) const {
;     ...
;         if (pn == 14) {
;             if (wc == 0 && fq == 0) {
;                 const f32x4 fb0 = *(const f32x4*)fbias, fb1 = *(const f32x4*)(fbias + 4);
; #pragma unroll
;                 for (int ai = 0; ai < 2; ++ai)
; #pragma unroll
;                     for (int m = 0; m < 4; ++m) {
;                         const int row = row0 + ai * 128 + m * 16;
;                         const f32x4 sv = *(const f32x4*)(ssq + (size_t)row * 16), sv1 = *(const f32x4*)(ssq + (size_t)row * 16 + 4), sv2 = *(const f32x4*)(ssq + (size_t)row * 16 + 8), sv3 = *(const f32x4*)(ssq + (size_t)row * 16 + 12);
;                         const float st = ((sv[0] + sv[1]) + (sv[2] + sv[3])) + ((sv1[0] + sv1[1]) + (sv1[2] + sv1[3])) + ((sv2[0] + sv2[1]) + (sv2[2] + sv2[3])) + ((sv3[0] + sv3[1]) + (sv3[2] + sv3[3]));
;                         const float rs = __builtin_amdgcn_rsqf(st * (1.f / DM) + EPS);
;                         f32x4 a = acc[ai][0][m][0] * rs, b = acc[ai][0][m][1] * rs;
; #pragma unroll
;                         for (int i = 0; i < 4; ++i) { a[i] = logsig_f(a[i] + fb0[i]) * LOG2E; b[i] = logsig_f(b[i] + fb1[i]) * LOG2E; }
;                         *(f32x4*)(FF + (size_t)row * 8) = a; *(f32x4*)(FF + (size_t)row * 8 + 4) = b;
;                         asm volatile("" ::: "memory");
;                     }
.LBB0_420:
	s_and_saveexec_b64 s[10:11], s[38:39]
	s_cbranch_execz .LBB0_422
	v_ashrrev_i32_e32 v167, 31, v166
	v_lshlrev_b64 v[72:73], 6, v[166:167]
	v_lshl_add_u64 v[84:85], s[82:83], 0, v[72:73]
	global_load_dwordx4 v[64:67], v193, s[34:35] offset:16
	global_load_dwordx4 v[68:71], v193, s[34:35]
	flat_load_dwordx4 v[72:75], v[84:85]
	flat_load_dwordx4 v[76:79], v[84:85] offset:16
	flat_load_dwordx4 v[80:83], v[84:85] offset:32
	s_nop 0
	flat_load_dwordx4 v[84:87], v[84:85] offset:48
	s_mov_b32 s2, 0x3fb8aa3b
	s_waitcnt vmcnt(0) lgkmcnt(0)
	v_mov_b32_e32 v88, v73
	v_mov_b32_e32 v89, v74
	v_mov_b32_e32 v73, v75
	v_mov_b32_e32 v74, v77
	v_mov_b32_e32 v75, v78
	v_mov_b32_e32 v77, v79
	v_pk_add_f32 v[72:73], v[88:89], v[72:73]
	v_pk_add_f32 v[74:75], v[74:75], v[76:77]
	v_pk_add_f32 v[72:73], v[72:73], v[72:73] op_sel:[0,1] op_sel_hi:[1,0]
	v_pk_add_f32 v[74:75], v[74:75], v[74:75] op_sel:[0,1] op_sel_hi:[1,0]
	v_add_f32_e32 v76, v80, v81
	v_add_f32_e32 v78, v82, v83
	v_mov_b32_e32 v73, v84
	v_mov_b32_e32 v75, v85
	v_mov_b32_e32 v77, v86
	v_mov_b32_e32 v79, v87
	v_pk_add_f32 v[72:73], v[72:73], v[74:75]
	v_pk_add_f32 v[74:75], v[76:77], v[78:79]
	s_nop 0
	v_pk_add_f32 v[72:73], v[72:73], v[74:75]
	s_nop 0
	v_add_f32_e32 v72, v72, v73
	v_fmamk_f32 v72, v72, 0x3a800000, v212
	v_rsq_f32_e32 v72, v72
	s_nop 0
	v_pk_mul_f32 v[60:61], v[60:61], v[72:73] op_sel_hi:[1,0]
	v_pk_mul_f32 v[74:75], v[62:63], v[72:73] op_sel_hi:[1,0]
	v_pk_mul_f32 v[58:59], v[58:59], v[72:73] op_sel_hi:[1,0]
	v_pk_mul_f32 v[72:73], v[56:57], v[72:73] op_sel_hi:[1,0]
	v_add_f32_e32 v57, v68, v60
	v_min_f32_e32 v56, 0, v57
	v_mul_f32_e64 v57, |v57|, s57
	v_exp_f32_e32 v57, v57
	v_add_f32_e32 v61, v69, v61
	v_add_f32_e32 v73, v65, v73
	v_add_f32_e32 v57, 1.0, v57
	v_log_f32_e32 v57, v57
	s_nop 0
	v_mul_f32_e32 v60, 0x3f317217, v57
	v_fma_f32 v60, v57, s52, -v60
	v_fmac_f32_e32 v60, 0x3377d1cf, v57
	v_fmac_f32_e32 v60, 0x3f317217, v57
	v_mov_b32_e32 v62, v60
	v_add_f32_e32 v57, v64, v72
	v_min_f32_e32 v60, 0, v57
	v_mul_f32_e64 v57, |v57|, s57
	v_exp_f32_e32 v57, v57
	s_nop 0
	v_add_f32_e32 v57, 1.0, v57
	v_log_f32_e32 v57, v57
	s_nop 0
	v_mul_f32_e32 v63, 0x3f317217, v57
	v_fma_f32 v63, v57, s52, -v63
	v_fmac_f32_e32 v63, 0x3377d1cf, v57
	v_fmac_f32_e32 v63, 0x3f317217, v57
	v_mov_b32_e32 v72, v63
	v_min_f32_e32 v57, 0, v61
	v_mul_f32_e64 v61, |v61|, s57
	v_exp_f32_e32 v61, v61
	s_nop 0
	v_add_f32_e32 v61, 1.0, v61
	v_log_f32_e32 v61, v61
	s_nop 0
	v_mul_f32_e32 v63, 0x3f317217, v61
	v_fma_f32 v63, v61, s52, -v63
	v_fmac_f32_e32 v63, 0x3377d1cf, v61
	v_fmac_f32_e32 v63, 0x3f317217, v61
	v_mov_b32_e32 v63, v63
	v_min_f32_e32 v61, 0, v73
	v_mul_f32_e64 v73, |v73|, s57
	v_exp_f32_e32 v73, v73
	v_pk_add_f32 v[56:57], v[56:57], v[62:63] neg_lo:[0,1] neg_hi:[0,1]
	v_add_f32_e32 v73, 1.0, v73
	v_log_f32_e32 v73, v73
	s_nop 0
	v_mul_f32_e32 v76, 0x3f317217, v73
	v_fma_f32 v76, v73, s52, -v76
	v_fmac_f32_e32 v76, 0x3377d1cf, v73
	v_fmac_f32_e32 v76, 0x3f317217, v73
	v_mov_b32_e32 v73, v76
	v_add_f32_e32 v76, v70, v74
	v_min_f32_e32 v74, 0, v76
	v_mul_f32_e64 v76, |v76|, s57
	v_exp_f32_e32 v76, v76
	s_nop 0
	v_add_f32_e32 v76, 1.0, v76
	v_log_f32_e32 v76, v76
	s_nop 0
	v_mul_f32_e32 v77, 0x3f317217, v76
	v_fma_f32 v77, v76, s52, -v77
	v_fmac_f32_e32 v77, 0x3377d1cf, v76
	v_fmac_f32_e32 v77, 0x3f317217, v76
	v_mov_b32_e32 v76, v77
	v_add_f32_e32 v77, v66, v58
	v_min_f32_e32 v58, 0, v77
	v_mul_f32_e64 v77, |v77|, s57
	v_exp_f32_e32 v77, v77
	s_nop 0
	v_add_f32_e32 v77, 1.0, v77
	v_log_f32_e32 v77, v77
	s_nop 0
	v_mul_f32_e32 v78, 0x3f317217, v77
	v_fma_f32 v78, v77, s52, -v78
	v_fmac_f32_e32 v78, 0x3377d1cf, v77
	v_fmac_f32_e32 v78, 0x3f317217, v77
	v_mov_b32_e32 v78, v78
	v_add_f32_e32 v77, v71, v75
	v_min_f32_e32 v75, 0, v77
	v_mul_f32_e64 v77, |v77|, s57
	v_exp_f32_e32 v77, v77
	s_nop 0
	v_add_f32_e32 v77, 1.0, v77
	v_log_f32_e32 v77, v77
	s_nop 0
	v_mul_f32_e32 v79, 0x3f317217, v77
	v_fma_f32 v79, v77, s52, -v79
	v_fmac_f32_e32 v79, 0x3377d1cf, v77
	v_fmac_f32_e32 v79, 0x3f317217, v77
	v_mov_b32_e32 v77, v79
	v_pk_add_f32 v[62:63], v[74:75], v[76:77] neg_lo:[0,1] neg_hi:[0,1]
	v_pk_mul_f32 v[74:75], v[56:57], s[2:3] op_sel_hi:[1,0]
	v_add_f32_e32 v56, v67, v59
	v_min_f32_e32 v59, 0, v56
	v_mul_f32_e64 v56, |v56|, s57
	v_exp_f32_e32 v56, v56
	v_pk_mul_f32 v[76:77], v[62:63], s[2:3] op_sel_hi:[1,0]
	v_add_f32_e32 v56, 1.0, v56
	v_log_f32_e32 v56, v56
	s_nop 0
	v_mul_f32_e32 v57, 0x3f317217, v56
	v_fma_f32 v57, v56, s52, -v57
	v_fmac_f32_e32 v57, 0x3377d1cf, v56
	v_fmac_f32_e32 v57, 0x3f317217, v56
	v_mov_b32_e32 v79, v57
	v_pk_add_f32 v[56:57], v[60:61], v[72:73] neg_lo:[0,1] neg_hi:[0,1]
	v_lshlrev_b64 v[60:61], 5, v[166:167]
	v_pk_add_f32 v[58:59], v[58:59], v[78:79] neg_lo:[0,1] neg_hi:[0,1]
	v_pk_mul_f32 v[56:57], v[56:57], s[2:3] op_sel_hi:[1,0]
	v_lshl_add_u64 v[60:61], s[42:43], 0, v[60:61]
	v_pk_mul_f32 v[58:59], v[58:59], s[2:3] op_sel_hi:[1,0]
	global_store_dwordx4 v[60:61], v[74:77], off
	global_store_dwordx4 v[60:61], v[56:59], off offset:16
	s_nop 1
	v_or_b32_e32 v56, 16, v166
	v_ashrrev_i32_e32 v57, 31, v56
	v_lshlrev_b64 v[58:59], 6, v[56:57]
	v_lshl_add_u64 v[62:63], s[82:83], 0, v[58:59]
	flat_load_dwordx4 v[58:61], v[62:63]
	flat_load_dwordx4 v[72:75], v[62:63] offset:16
	flat_load_dwordx4 v[76:79], v[62:63] offset:32
	flat_load_dwordx4 v[80:83], v[62:63] offset:48
	s_waitcnt vmcnt(0) lgkmcnt(0)
; __device__ __forceinline__ float logsig_f(float x) { return fminf(x, 0.f) - __logf(1.f + __expf(-fabsf(x))); }
;     __device__ __forceinline__ void operator()(const f32x4 (&acc)[2][2][4][2], const pg8::Unit& u, int wr, int wc, int fr, int fq) const {
;     ...
;                     for (int m = 0; m < 4; ++m) {
;                         const int row = row0 + ai * 128 + m * 16;
;                         const f32x4 sv = *(const f32x4*)(ssq + (size_t)row * 16), sv1 = *(const f32x4*)(ssq + (size_t)row * 16 + 4), sv2 = *(const f32x4*)(ssq + (size_t)row * 16 + 8), sv3 = *(const f32x4*)(ssq + (size_t)row * 16 + 12);
;                         const float st = ((sv[0] + sv[1]) + (sv[2] + sv[3])) + ((sv1[0] + sv1[1]) + (sv1[2] + sv1[3])) + ((sv2[0] + sv2[1]) + (sv2[2] + sv2[3])) + ((sv3[0] + sv3[1]) + (sv3[2] + sv3[3]));
;                         const float rs = __builtin_amdgcn_rsqf(st * (1.f / DM) + EPS);
;                         f32x4 a = acc[ai][0][m][0] * rs, b = acc[ai][0][m][1] * rs;
; #pragma unroll
;                         for (int i = 0; i < 4; ++i) { a[i] = logsig_f(a[i] + fb0[i]) * LOG2E; b[i] = logsig_f(b[i] + fb1[i]) * LOG2E; }
;                         *(f32x4*)(FF + (size_t)row * 8) = a; *(f32x4*)(FF + (size_t)row * 8 + 4) = b;
;                         asm volatile("" ::: "memory");
	v_mov_b32_e32 v62, v59
	v_mov_b32_e32 v63, v60
	v_mov_b32_e32 v59, v61
	v_mov_b32_e32 v60, v73
	v_mov_b32_e32 v61, v74
	v_mov_b32_e32 v73, v75
	v_pk_add_f32 v[58:59], v[62:63], v[58:59]
	v_pk_add_f32 v[60:61], v[60:61], v[72:73]
	v_pk_add_f32 v[58:59], v[58:59], v[58:59] op_sel:[0,1] op_sel_hi:[1,0]
	v_pk_add_f32 v[60:61], v[60:61], v[60:61] op_sel:[0,1] op_sel_hi:[1,0]
	v_add_f32_e32 v62, v76, v77
	v_add_f32_e32 v72, v78, v79
	v_mov_b32_e32 v59, v80
	v_mov_b32_e32 v61, v81
	v_mov_b32_e32 v63, v82
	v_mov_b32_e32 v73, v83
	v_pk_add_f32 v[58:59], v[58:59], v[60:61]
	v_pk_add_f32 v[60:61], v[62:63], v[72:73]
	s_nop 0
	v_pk_add_f32 v[58:59], v[58:59], v[60:61]
	s_nop 0
	v_add_f32_e32 v58, v58, v59
	v_fmamk_f32 v58, v58, 0x3a800000, v212
	v_rsq_f32_e32 v60, v58
	s_nop 0
	v_pk_mul_f32 v[52:53], v[52:53], v[60:61] op_sel_hi:[1,0]
	v_pk_mul_f32 v[58:59], v[54:55], v[60:61] op_sel_hi:[1,0]
	v_add_f32_e32 v54, v68, v52
	v_min_f32_e32 v52, 0, v54
	v_mul_f32_e64 v54, |v54|, s57
	v_exp_f32_e32 v54, v54
	v_pk_mul_f32 v[48:49], v[48:49], v[60:61] op_sel_hi:[1,0]
	v_pk_mul_f32 v[50:51], v[50:51], v[60:61] op_sel_hi:[1,0]
	v_add_f32_e32 v54, 1.0, v54
	v_log_f32_e32 v54, v54
	s_nop 0
	v_mul_f32_e32 v55, 0x3f317217, v54
	v_fma_f32 v55, v54, s52, -v55
	v_fmac_f32_e32 v55, 0x3377d1cf, v54
	v_fmac_f32_e32 v55, 0x3f317217, v54
	v_mov_b32_e32 v60, v55
	v_add_f32_e32 v54, v64, v48
	v_min_f32_e32 v48, 0, v54
	v_mul_f32_e64 v54, |v54|, s57
	v_exp_f32_e32 v54, v54
	s_nop 0
	v_add_f32_e32 v54, 1.0, v54
	v_log_f32_e32 v54, v54
	s_nop 0
	v_mul_f32_e32 v55, 0x3f317217, v54
	v_fma_f32 v55, v54, s52, -v55
	v_fmac_f32_e32 v55, 0x3377d1cf, v54
	v_fmac_f32_e32 v55, 0x3f317217, v54
	v_mov_b32_e32 v54, v55
	v_add_f32_e32 v55, v69, v53
	v_min_f32_e32 v53, 0, v55
	v_mul_f32_e64 v55, |v55|, s57
	v_exp_f32_e32 v55, v55
	s_nop 0
	v_add_f32_e32 v55, 1.0, v55
	v_log_f32_e32 v55, v55
	s_nop 0
	v_mul_f32_e32 v61, 0x3f317217, v55
	v_fma_f32 v61, v55, s52, -v61
	v_fmac_f32_e32 v61, 0x3377d1cf, v55
	v_fmac_f32_e32 v61, 0x3f317217, v55
	v_mov_b32_e32 v61, v61
	v_add_f32_e32 v55, v65, v49
	v_min_f32_e32 v49, 0, v55
	v_mul_f32_e64 v55, |v55|, s57
	v_exp_f32_e32 v55, v55
	v_pk_add_f32 v[52:53], v[52:53], v[60:61] neg_lo:[0,1] neg_hi:[0,1]
	v_add_f32_e32 v55, 1.0, v55
	v_log_f32_e32 v55, v55
	s_nop 0
	v_mul_f32_e32 v62, 0x3f317217, v55
	v_fma_f32 v62, v55, s52, -v62
	v_fmac_f32_e32 v62, 0x3377d1cf, v55
	v_fmac_f32_e32 v62, 0x3f317217, v55
	v_mov_b32_e32 v55, v62
	v_add_f32_e32 v62, v70, v58
	v_min_f32_e32 v58, 0, v62
	v_mul_f32_e64 v62, |v62|, s57
	v_exp_f32_e32 v62, v62
	v_pk_add_f32 v[48:49], v[48:49], v[54:55] neg_lo:[0,1] neg_hi:[0,1]
	v_add_f32_e32 v62, 1.0, v62
	v_pk_mul_f32 v[48:49], v[48:49], s[2:3] op_sel_hi:[1,0]
	s_nop 0
	v_log_f32_e32 v62, v62
	s_nop 0
	v_mul_f32_e32 v63, 0x3f317217, v62
	v_fma_f32 v63, v62, s52, -v63
	v_fmac_f32_e32 v63, 0x3377d1cf, v62
	v_fmac_f32_e32 v63, 0x3f317217, v62
	v_mov_b32_e32 v62, v63
	v_add_f32_e32 v63, v66, v50
	v_min_f32_e32 v50, 0, v63
	v_mul_f32_e64 v63, |v63|, s57
	v_exp_f32_e32 v63, v63
	s_nop 0
	v_add_f32_e32 v63, 1.0, v63
	v_log_f32_e32 v63, v63
	s_nop 0
	v_mul_f32_e32 v72, 0x3f317217, v63
	v_fma_f32 v72, v63, s52, -v72
	v_fmac_f32_e32 v72, 0x3377d1cf, v63
	v_fmac_f32_e32 v72, 0x3f317217, v63
	v_mov_b32_e32 v72, v72
	v_add_f32_e32 v63, v71, v59
	v_min_f32_e32 v59, 0, v63
	v_mul_f32_e64 v63, |v63|, s57
	v_exp_f32_e32 v63, v63
	s_nop 0
	v_add_f32_e32 v63, 1.0, v63
	v_log_f32_e32 v63, v63
	s_nop 0
	v_mul_f32_e32 v73, 0x3f317217, v63
	v_fma_f32 v73, v63, s52, -v73
	v_fmac_f32_e32 v73, 0x3377d1cf, v63
	v_fmac_f32_e32 v73, 0x3f317217, v63
	v_mov_b32_e32 v63, v73
	v_pk_add_f32 v[58:59], v[58:59], v[62:63] neg_lo:[0,1] neg_hi:[0,1]
	s_nop 0
	v_pk_mul_f32 v[60:61], v[58:59], s[2:3] op_sel_hi:[1,0]
	v_pk_mul_f32 v[58:59], v[52:53], s[2:3] op_sel_hi:[1,0]
	v_add_f32_e32 v52, v67, v51
	v_min_f32_e32 v51, 0, v52
	v_mul_f32_e64 v52, |v52|, s57
	v_exp_f32_e32 v52, v52
	s_nop 0
	v_add_f32_e32 v52, 1.0, v52
	v_log_f32_e32 v52, v52
	s_nop 0
	v_mul_f32_e32 v53, 0x3f317217, v52
	v_fma_f32 v53, v52, s52, -v53
	v_fmac_f32_e32 v53, 0x3377d1cf, v52
	v_fmac_f32_e32 v53, 0x3f317217, v52
	v_mov_b32_e32 v73, v53
	v_lshlrev_b64 v[52:53], 5, v[56:57]
	v_pk_add_f32 v[50:51], v[50:51], v[72:73] neg_lo:[0,1] neg_hi:[0,1]
	v_lshl_add_u64 v[52:53], s[42:43], 0, v[52:53]
	v_pk_mul_f32 v[50:51], v[50:51], s[2:3] op_sel_hi:[1,0]
	global_store_dwordx4 v[52:53], v[58:61], off
	global_store_dwordx4 v[52:53], v[48:51], off offset:16
	s_nop 1
	v_or_b32_e32 v48, 32, v166
	v_ashrrev_i32_e32 v49, 31, v48
	v_lshlrev_b64 v[50:51], 6, v[48:49]
	v_lshl_add_u64 v[62:63], s[82:83], 0, v[50:51]
	flat_load_dwordx4 v[50:53], v[62:63]
	flat_load_dwordx4 v[54:57], v[62:63] offset:16
	flat_load_dwordx4 v[58:61], v[62:63] offset:32
	flat_load_dwordx4 v[72:75], v[62:63] offset:48
	s_waitcnt vmcnt(0) lgkmcnt(0)
; __device__ __forceinline__ float logsig_f(float x) { return fminf(x, 0.f) - __logf(1.f + __expf(-fabsf(x))); }
;     __device__ __forceinline__ void operator()(const f32x4 (&acc)[2][2][4][2], const pg8::Unit& u, int wr, int wc, int fr, int fq) const {
;     ...
;                     for (int m = 0; m < 4; ++m) {
;                         const int row = row0 + ai * 128 + m * 16;
;                         const f32x4 sv = *(const f32x4*)(ssq + (size_t)row * 16), sv1 = *(const f32x4*)(ssq + (size_t)row * 16 + 4), sv2 = *(const f32x4*)(ssq + (size_t)row * 16 + 8), sv3 = *(const f32x4*)(ssq + (size_t)row * 16 + 12);
;                         const float st = ((sv[0] + sv[1]) + (sv[2] + sv[3])) + ((sv1[0] + sv1[1]) + (sv1[2] + sv1[3])) + ((sv2[0] + sv2[1]) + (sv2[2] + sv2[3])) + ((sv3[0] + sv3[1]) + (sv3[2] + sv3[3]));
;                         const float rs = __builtin_amdgcn_rsqf(st * (1.f / DM) + EPS);
;                         f32x4 a = acc[ai][0][m][0] * rs, b = acc[ai][0][m][1] * rs;
; #pragma unroll
;                         for (int i = 0; i < 4; ++i) { a[i] = logsig_f(a[i] + fb0[i]) * LOG2E; b[i] = logsig_f(b[i] + fb1[i]) * LOG2E; }
;                         *(f32x4*)(FF + (size_t)row * 8) = a; *(f32x4*)(FF + (size_t)row * 8 + 4) = b;
;                         asm volatile("" ::: "memory");
	v_mov_b32_e32 v62, v51
	v_mov_b32_e32 v63, v52
	v_mov_b32_e32 v51, v53
	v_mov_b32_e32 v52, v55
	v_mov_b32_e32 v53, v56
	v_mov_b32_e32 v55, v57
	v_pk_add_f32 v[50:51], v[62:63], v[50:51]
	v_pk_add_f32 v[52:53], v[52:53], v[54:55]
	v_pk_add_f32 v[50:51], v[50:51], v[50:51] op_sel:[0,1] op_sel_hi:[1,0]
	v_pk_add_f32 v[52:53], v[52:53], v[52:53] op_sel:[0,1] op_sel_hi:[1,0]
	v_add_f32_e32 v54, v58, v59
	v_add_f32_e32 v56, v60, v61
	v_mov_b32_e32 v51, v72
	v_mov_b32_e32 v53, v73
	v_mov_b32_e32 v55, v74
	v_mov_b32_e32 v57, v75
	v_pk_add_f32 v[50:51], v[50:51], v[52:53]
	v_pk_add_f32 v[52:53], v[54:55], v[56:57]
	s_nop 0
	v_pk_add_f32 v[50:51], v[50:51], v[52:53]
	s_nop 0
	v_add_f32_e32 v50, v50, v51
	v_fmamk_f32 v50, v50, 0x3a800000, v212
	v_rsq_f32_e32 v52, v50
	s_nop 0
	v_pk_mul_f32 v[44:45], v[44:45], v[52:53] op_sel_hi:[1,0]
	v_pk_mul_f32 v[50:51], v[46:47], v[52:53] op_sel_hi:[1,0]
	v_add_f32_e32 v46, v68, v44
	v_min_f32_e32 v44, 0, v46
	v_mul_f32_e64 v46, |v46|, s57
	v_exp_f32_e32 v46, v46
	v_pk_mul_f32 v[40:41], v[40:41], v[52:53] op_sel_hi:[1,0]
	v_pk_mul_f32 v[42:43], v[42:43], v[52:53] op_sel_hi:[1,0]
	v_add_f32_e32 v46, 1.0, v46
	v_log_f32_e32 v46, v46
	s_nop 0
	v_mul_f32_e32 v47, 0x3f317217, v46
	v_fma_f32 v47, v46, s52, -v47
	v_fmac_f32_e32 v47, 0x3377d1cf, v46
	v_fmac_f32_e32 v47, 0x3f317217, v46
	v_mov_b32_e32 v52, v47
	v_add_f32_e32 v46, v64, v40
	v_min_f32_e32 v40, 0, v46
	v_mul_f32_e64 v46, |v46|, s57
	v_exp_f32_e32 v46, v46
	s_nop 0
	v_add_f32_e32 v46, 1.0, v46
	v_log_f32_e32 v46, v46
	s_nop 0
	v_mul_f32_e32 v47, 0x3f317217, v46
	v_fma_f32 v47, v46, s52, -v47
	v_fmac_f32_e32 v47, 0x3377d1cf, v46
	v_fmac_f32_e32 v47, 0x3f317217, v46
	v_mov_b32_e32 v46, v47
	v_add_f32_e32 v47, v69, v45
	v_min_f32_e32 v45, 0, v47
	v_mul_f32_e64 v47, |v47|, s57
	v_exp_f32_e32 v47, v47
	s_nop 0
	v_add_f32_e32 v47, 1.0, v47
	v_log_f32_e32 v47, v47
	s_nop 0
	v_mul_f32_e32 v53, 0x3f317217, v47
	v_fma_f32 v53, v47, s52, -v53
	v_fmac_f32_e32 v53, 0x3377d1cf, v47
	v_fmac_f32_e32 v53, 0x3f317217, v47
	v_mov_b32_e32 v53, v53
	v_add_f32_e32 v47, v65, v41
	v_min_f32_e32 v41, 0, v47
	v_mul_f32_e64 v47, |v47|, s57
	v_exp_f32_e32 v47, v47
	v_pk_add_f32 v[44:45], v[44:45], v[52:53] neg_lo:[0,1] neg_hi:[0,1]
	v_add_f32_e32 v47, 1.0, v47
	v_log_f32_e32 v47, v47
	s_nop 0
	v_mul_f32_e32 v54, 0x3f317217, v47
	v_fma_f32 v54, v47, s52, -v54
	v_fmac_f32_e32 v54, 0x3377d1cf, v47
	v_fmac_f32_e32 v54, 0x3f317217, v47
	v_mov_b32_e32 v47, v54
	v_add_f32_e32 v54, v70, v50
	v_min_f32_e32 v50, 0, v54
	v_mul_f32_e64 v54, |v54|, s57
	v_exp_f32_e32 v54, v54
	v_pk_add_f32 v[40:41], v[40:41], v[46:47] neg_lo:[0,1] neg_hi:[0,1]
	v_add_f32_e32 v54, 1.0, v54
	v_pk_mul_f32 v[40:41], v[40:41], s[2:3] op_sel_hi:[1,0]
	s_nop 0
	v_log_f32_e32 v54, v54
	s_nop 0
	v_mul_f32_e32 v55, 0x3f317217, v54
	v_fma_f32 v55, v54, s52, -v55
	v_fmac_f32_e32 v55, 0x3377d1cf, v54
	v_fmac_f32_e32 v55, 0x3f317217, v54
	v_mov_b32_e32 v54, v55
	v_add_f32_e32 v55, v66, v42
	v_min_f32_e32 v42, 0, v55
	v_mul_f32_e64 v55, |v55|, s57
	v_exp_f32_e32 v55, v55
	s_nop 0
	v_add_f32_e32 v55, 1.0, v55
	v_log_f32_e32 v55, v55
	s_nop 0
	v_mul_f32_e32 v56, 0x3f317217, v55
	v_fma_f32 v56, v55, s52, -v56
	v_fmac_f32_e32 v56, 0x3377d1cf, v55
	v_fmac_f32_e32 v56, 0x3f317217, v55
	v_mov_b32_e32 v56, v56
	v_add_f32_e32 v55, v71, v51
	v_min_f32_e32 v51, 0, v55
	v_mul_f32_e64 v55, |v55|, s57
	v_exp_f32_e32 v55, v55
	s_nop 0
	v_add_f32_e32 v55, 1.0, v55
	v_log_f32_e32 v55, v55
	s_nop 0
	v_mul_f32_e32 v57, 0x3f317217, v55
	v_fma_f32 v57, v55, s52, -v57
	v_fmac_f32_e32 v57, 0x3377d1cf, v55
	v_fmac_f32_e32 v57, 0x3f317217, v55
	v_mov_b32_e32 v55, v57
	v_pk_add_f32 v[50:51], v[50:51], v[54:55] neg_lo:[0,1] neg_hi:[0,1]
	s_nop 0
	v_pk_mul_f32 v[52:53], v[50:51], s[2:3] op_sel_hi:[1,0]
	v_pk_mul_f32 v[50:51], v[44:45], s[2:3] op_sel_hi:[1,0]
	v_add_f32_e32 v44, v67, v43
	v_min_f32_e32 v43, 0, v44
	v_mul_f32_e64 v44, |v44|, s57
	v_exp_f32_e32 v44, v44
	s_nop 0
	v_add_f32_e32 v44, 1.0, v44
	v_log_f32_e32 v44, v44
	s_nop 0
	v_mul_f32_e32 v45, 0x3f317217, v44
	v_fma_f32 v45, v44, s52, -v45
	v_fmac_f32_e32 v45, 0x3377d1cf, v44
	v_fmac_f32_e32 v45, 0x3f317217, v44
	v_mov_b32_e32 v57, v45
	v_lshlrev_b64 v[44:45], 5, v[48:49]
	v_pk_add_f32 v[42:43], v[42:43], v[56:57] neg_lo:[0,1] neg_hi:[0,1]
	v_lshl_add_u64 v[44:45], s[42:43], 0, v[44:45]
	v_pk_mul_f32 v[42:43], v[42:43], s[2:3] op_sel_hi:[1,0]
	global_store_dwordx4 v[44:45], v[50:53], off
	global_store_dwordx4 v[44:45], v[40:43], off offset:16
	s_nop 1
	v_or_b32_e32 v40, 48, v166
	v_ashrrev_i32_e32 v41, 31, v40
	v_lshlrev_b64 v[42:43], 6, v[40:41]
	v_lshl_add_u64 v[54:55], s[82:83], 0, v[42:43]
	flat_load_dwordx4 v[42:45], v[54:55]
	flat_load_dwordx4 v[46:49], v[54:55] offset:16
	flat_load_dwordx4 v[50:53], v[54:55] offset:32
	s_nop 0
	flat_load_dwordx4 v[54:57], v[54:55] offset:48
	s_waitcnt vmcnt(0) lgkmcnt(0)
; __device__ __forceinline__ float logsig_f(float x) { return fminf(x, 0.f) - __logf(1.f + __expf(-fabsf(x))); }
;     __device__ __forceinline__ void operator()(const f32x4 (&acc)[2][2][4][2], const pg8::Unit& u, int wr, int wc, int fr, int fq) const {
;     ...
;                     for (int m = 0; m < 4; ++m) {
;                         const int row = row0 + ai * 128 + m * 16;
;                         const f32x4 sv = *(const f32x4*)(ssq + (size_t)row * 16), sv1 = *(const f32x4*)(ssq + (size_t)row * 16 + 4), sv2 = *(const f32x4*)(ssq + (size_t)row * 16 + 8), sv3 = *(const f32x4*)(ssq + (size_t)row * 16 + 12);
;                         const float st = ((sv[0] + sv[1]) + (sv[2] + sv[3])) + ((sv1[0] + sv1[1]) + (sv1[2] + sv1[3])) + ((sv2[0] + sv2[1]) + (sv2[2] + sv2[3])) + ((sv3[0] + sv3[1]) + (sv3[2] + sv3[3]));
;                         const float rs = __builtin_amdgcn_rsqf(st * (1.f / DM) + EPS);
;                         f32x4 a = acc[ai][0][m][0] * rs, b = acc[ai][0][m][1] * rs;
; #pragma unroll
;                         for (int i = 0; i < 4; ++i) { a[i] = logsig_f(a[i] + fb0[i]) * LOG2E; b[i] = logsig_f(b[i] + fb1[i]) * LOG2E; }
;                         *(f32x4*)(FF + (size_t)row * 8) = a; *(f32x4*)(FF + (size_t)row * 8 + 4) = b;
;                         asm volatile("" ::: "memory");
	v_mov_b32_e32 v58, v43
	v_mov_b32_e32 v59, v44
	v_mov_b32_e32 v43, v45
	v_mov_b32_e32 v44, v47
	v_mov_b32_e32 v45, v48
	v_mov_b32_e32 v47, v49
	v_pk_add_f32 v[42:43], v[58:59], v[42:43]
	v_pk_add_f32 v[44:45], v[44:45], v[46:47]
	v_pk_add_f32 v[42:43], v[42:43], v[42:43] op_sel:[0,1] op_sel_hi:[1,0]
	v_pk_add_f32 v[44:45], v[44:45], v[44:45] op_sel:[0,1] op_sel_hi:[1,0]
	v_add_f32_e32 v46, v50, v51
	v_add_f32_e32 v48, v52, v53
	v_mov_b32_e32 v43, v54
	v_mov_b32_e32 v45, v55
	v_mov_b32_e32 v47, v56
	v_mov_b32_e32 v49, v57
	v_pk_add_f32 v[42:43], v[42:43], v[44:45]
	v_pk_add_f32 v[44:45], v[46:47], v[48:49]
	s_nop 0
	v_pk_add_f32 v[42:43], v[42:43], v[44:45]
	s_nop 0
	v_add_f32_e32 v42, v42, v43
	v_fmamk_f32 v42, v42, 0x3a800000, v212
	v_rsq_f32_e32 v44, v42
	s_nop 0
	v_pk_mul_f32 v[36:37], v[36:37], v[44:45] op_sel_hi:[1,0]
	v_pk_mul_f32 v[42:43], v[38:39], v[44:45] op_sel_hi:[1,0]
	v_add_f32_e32 v38, v68, v36
	v_min_f32_e32 v36, 0, v38
	v_mul_f32_e64 v38, |v38|, s57
	v_exp_f32_e32 v38, v38
	v_pk_mul_f32 v[32:33], v[32:33], v[44:45] op_sel_hi:[1,0]
	v_pk_mul_f32 v[34:35], v[34:35], v[44:45] op_sel_hi:[1,0]
	v_add_f32_e32 v38, 1.0, v38
	v_log_f32_e32 v38, v38
	s_nop 0
	v_mul_f32_e32 v39, 0x3f317217, v38
	v_fma_f32 v39, v38, s52, -v39
	v_fmac_f32_e32 v39, 0x3377d1cf, v38
	v_fmac_f32_e32 v39, 0x3f317217, v38
	v_mov_b32_e32 v44, v39
	v_add_f32_e32 v38, v64, v32
	v_min_f32_e32 v32, 0, v38
	v_mul_f32_e64 v38, |v38|, s57
	v_exp_f32_e32 v38, v38
	s_nop 0
	v_add_f32_e32 v38, 1.0, v38
	v_log_f32_e32 v38, v38
	s_nop 0
	v_mul_f32_e32 v39, 0x3f317217, v38
	v_fma_f32 v39, v38, s52, -v39
	v_fmac_f32_e32 v39, 0x3377d1cf, v38
	v_fmac_f32_e32 v39, 0x3f317217, v38
	v_mov_b32_e32 v38, v39
	v_add_f32_e32 v39, v69, v37
	v_min_f32_e32 v37, 0, v39
	v_mul_f32_e64 v39, |v39|, s57
	v_exp_f32_e32 v39, v39
	s_nop 0
	v_add_f32_e32 v39, 1.0, v39
	v_log_f32_e32 v39, v39
	s_nop 0
	v_mul_f32_e32 v45, 0x3f317217, v39
	v_fma_f32 v45, v39, s52, -v45
	v_fmac_f32_e32 v45, 0x3377d1cf, v39
	v_fmac_f32_e32 v45, 0x3f317217, v39
	v_mov_b32_e32 v45, v45
	v_add_f32_e32 v39, v65, v33
	v_min_f32_e32 v33, 0, v39
	v_mul_f32_e64 v39, |v39|, s57
	v_exp_f32_e32 v39, v39
	v_pk_add_f32 v[36:37], v[36:37], v[44:45] neg_lo:[0,1] neg_hi:[0,1]
	v_add_f32_e32 v39, 1.0, v39
	v_log_f32_e32 v39, v39
	s_nop 0
	v_mul_f32_e32 v46, 0x3f317217, v39
	v_fma_f32 v46, v39, s52, -v46
	v_fmac_f32_e32 v46, 0x3377d1cf, v39
	v_fmac_f32_e32 v46, 0x3f317217, v39
	v_mov_b32_e32 v39, v46
	v_add_f32_e32 v46, v70, v42
	v_min_f32_e32 v42, 0, v46
	v_mul_f32_e64 v46, |v46|, s57
	v_exp_f32_e32 v46, v46
	v_pk_add_f32 v[32:33], v[32:33], v[38:39] neg_lo:[0,1] neg_hi:[0,1]
	v_add_f32_e32 v46, 1.0, v46
	v_pk_mul_f32 v[32:33], v[32:33], s[2:3] op_sel_hi:[1,0]
	s_nop 0
	v_log_f32_e32 v46, v46
	s_nop 0
	v_mul_f32_e32 v47, 0x3f317217, v46
	v_fma_f32 v47, v46, s52, -v47
	v_fmac_f32_e32 v47, 0x3377d1cf, v46
	v_fmac_f32_e32 v47, 0x3f317217, v46
	v_mov_b32_e32 v46, v47
	v_add_f32_e32 v47, v66, v34
	v_min_f32_e32 v34, 0, v47
	v_mul_f32_e64 v47, |v47|, s57
	v_exp_f32_e32 v47, v47
	s_nop 0
	v_add_f32_e32 v47, 1.0, v47
	v_log_f32_e32 v47, v47
	s_nop 0
	v_mul_f32_e32 v48, 0x3f317217, v47
	v_fma_f32 v48, v47, s52, -v48
	v_fmac_f32_e32 v48, 0x3377d1cf, v47
	v_fmac_f32_e32 v48, 0x3f317217, v47
	v_mov_b32_e32 v48, v48
	v_add_f32_e32 v47, v71, v43
	v_min_f32_e32 v43, 0, v47
	v_mul_f32_e64 v47, |v47|, s57
	v_exp_f32_e32 v47, v47
	s_nop 0
	v_add_f32_e32 v47, 1.0, v47
	v_log_f32_e32 v47, v47
	s_nop 0
	v_mul_f32_e32 v49, 0x3f317217, v47
	v_fma_f32 v49, v47, s52, -v49
	v_fmac_f32_e32 v49, 0x3377d1cf, v47
	v_fmac_f32_e32 v49, 0x3f317217, v47
	v_mov_b32_e32 v47, v49
	v_pk_add_f32 v[42:43], v[42:43], v[46:47] neg_lo:[0,1] neg_hi:[0,1]
	s_nop 0
	v_pk_mul_f32 v[44:45], v[42:43], s[2:3] op_sel_hi:[1,0]
	v_pk_mul_f32 v[42:43], v[36:37], s[2:3] op_sel_hi:[1,0]
	v_add_f32_e32 v36, v67, v35
	v_min_f32_e32 v35, 0, v36
	v_mul_f32_e64 v36, |v36|, s57
	v_exp_f32_e32 v36, v36
	s_nop 0
	v_add_f32_e32 v36, 1.0, v36
	v_log_f32_e32 v36, v36
	s_nop 0
	v_mul_f32_e32 v37, 0x3f317217, v36
	v_fma_f32 v37, v36, s52, -v37
	v_fmac_f32_e32 v37, 0x3377d1cf, v36
	v_fmac_f32_e32 v37, 0x3f317217, v36
	v_mov_b32_e32 v49, v37
	v_lshlrev_b64 v[36:37], 5, v[40:41]
	v_pk_add_f32 v[34:35], v[34:35], v[48:49] neg_lo:[0,1] neg_hi:[0,1]
	v_lshl_add_u64 v[36:37], s[42:43], 0, v[36:37]
	v_pk_mul_f32 v[34:35], v[34:35], s[2:3] op_sel_hi:[1,0]
	global_store_dwordx4 v[36:37], v[42:45], off
	global_store_dwordx4 v[36:37], v[32:35], off offset:16
	s_nop 1
	v_add_u32_e32 v32, 0x80, v166
	v_ashrrev_i32_e32 v33, 31, v32
	v_lshlrev_b64 v[34:35], 6, v[32:33]
	v_lshl_add_u64 v[46:47], s[82:83], 0, v[34:35]
	flat_load_dwordx4 v[34:37], v[46:47]
	flat_load_dwordx4 v[38:41], v[46:47] offset:16
	flat_load_dwordx4 v[42:45], v[46:47] offset:32
	s_nop 0
	flat_load_dwordx4 v[46:49], v[46:47] offset:48
	s_waitcnt vmcnt(0) lgkmcnt(0)
; __device__ __forceinline__ float logsig_f(float x) { return fminf(x, 0.f) - __logf(1.f + __expf(-fabsf(x))); }
;     __device__ __forceinline__ void operator()(const f32x4 (&acc)[2][2][4][2], const pg8::Unit& u, int wr, int wc, int fr, int fq) const {
;     ...
;                     for (int m = 0; m < 4; ++m) {
;                         const int row = row0 + ai * 128 + m * 16;
;                         const f32x4 sv = *(const f32x4*)(ssq + (size_t)row * 16), sv1 = *(const f32x4*)(ssq + (size_t)row * 16 + 4), sv2 = *(const f32x4*)(ssq + (size_t)row * 16 + 8), sv3 = *(const f32x4*)(ssq + (size_t)row * 16 + 12);
;                         const float st = ((sv[0] + sv[1]) + (sv[2] + sv[3])) + ((sv1[0] + sv1[1]) + (sv1[2] + sv1[3])) + ((sv2[0] + sv2[1]) + (sv2[2] + sv2[3])) + ((sv3[0] + sv3[1]) + (sv3[2] + sv3[3]));
;                         const float rs = __builtin_amdgcn_rsqf(st * (1.f / DM) + EPS);
;                         f32x4 a = acc[ai][0][m][0] * rs, b = acc[ai][0][m][1] * rs;
; #pragma unroll
;                         for (int i = 0; i < 4; ++i) { a[i] = logsig_f(a[i] + fb0[i]) * LOG2E; b[i] = logsig_f(b[i] + fb1[i]) * LOG2E; }
;                         *(f32x4*)(FF + (size_t)row * 8) = a; *(f32x4*)(FF + (size_t)row * 8 + 4) = b;
;                         asm volatile("" ::: "memory");
	v_mov_b32_e32 v50, v35
	v_mov_b32_e32 v51, v36
	v_mov_b32_e32 v35, v37
	v_mov_b32_e32 v36, v39
	v_mov_b32_e32 v37, v40
	v_mov_b32_e32 v39, v41
	v_pk_add_f32 v[34:35], v[50:51], v[34:35]
	v_pk_add_f32 v[36:37], v[36:37], v[38:39]
	v_pk_add_f32 v[34:35], v[34:35], v[34:35] op_sel:[0,1] op_sel_hi:[1,0]
	v_pk_add_f32 v[36:37], v[36:37], v[36:37] op_sel:[0,1] op_sel_hi:[1,0]
	v_add_f32_e32 v38, v42, v43
	v_add_f32_e32 v40, v44, v45
	v_mov_b32_e32 v35, v46
	v_mov_b32_e32 v37, v47
	v_mov_b32_e32 v39, v48
	v_mov_b32_e32 v41, v49
	v_pk_add_f32 v[34:35], v[34:35], v[36:37]
	v_pk_add_f32 v[36:37], v[38:39], v[40:41]
	s_nop 0
	v_pk_add_f32 v[34:35], v[34:35], v[36:37]
	s_nop 0
	v_add_f32_e32 v34, v34, v35
	v_fmamk_f32 v34, v34, 0x3a800000, v212
	v_rsq_f32_e32 v36, v34
	s_nop 0
	v_pk_mul_f32 v[28:29], v[28:29], v[36:37] op_sel_hi:[1,0]
	v_pk_mul_f32 v[34:35], v[30:31], v[36:37] op_sel_hi:[1,0]
	v_add_f32_e32 v30, v68, v28
	v_min_f32_e32 v28, 0, v30
	v_mul_f32_e64 v30, |v30|, s57
	v_exp_f32_e32 v30, v30
	v_pk_mul_f32 v[24:25], v[24:25], v[36:37] op_sel_hi:[1,0]
	v_pk_mul_f32 v[26:27], v[26:27], v[36:37] op_sel_hi:[1,0]
	v_add_f32_e32 v30, 1.0, v30
	v_log_f32_e32 v30, v30
	s_nop 0
	v_mul_f32_e32 v31, 0x3f317217, v30
	v_fma_f32 v31, v30, s52, -v31
	v_fmac_f32_e32 v31, 0x3377d1cf, v30
	v_fmac_f32_e32 v31, 0x3f317217, v30
	v_mov_b32_e32 v36, v31
	v_add_f32_e32 v30, v64, v24
	v_min_f32_e32 v24, 0, v30
	v_mul_f32_e64 v30, |v30|, s57
	v_exp_f32_e32 v30, v30
	s_nop 0
	v_add_f32_e32 v30, 1.0, v30
	v_log_f32_e32 v30, v30
	s_nop 0
	v_mul_f32_e32 v31, 0x3f317217, v30
	v_fma_f32 v31, v30, s52, -v31
	v_fmac_f32_e32 v31, 0x3377d1cf, v30
	v_fmac_f32_e32 v31, 0x3f317217, v30
	v_mov_b32_e32 v30, v31
	v_add_f32_e32 v31, v69, v29
	v_min_f32_e32 v29, 0, v31
	v_mul_f32_e64 v31, |v31|, s57
	v_exp_f32_e32 v31, v31
	s_nop 0
	v_add_f32_e32 v31, 1.0, v31
	v_log_f32_e32 v31, v31
	s_nop 0
	v_mul_f32_e32 v37, 0x3f317217, v31
	v_fma_f32 v37, v31, s52, -v37
	v_fmac_f32_e32 v37, 0x3377d1cf, v31
	v_fmac_f32_e32 v37, 0x3f317217, v31
	v_mov_b32_e32 v37, v37
	v_add_f32_e32 v31, v65, v25
	v_min_f32_e32 v25, 0, v31
	v_mul_f32_e64 v31, |v31|, s57
	v_exp_f32_e32 v31, v31
	v_pk_add_f32 v[28:29], v[28:29], v[36:37] neg_lo:[0,1] neg_hi:[0,1]
	v_add_f32_e32 v31, 1.0, v31
	v_log_f32_e32 v31, v31
	s_nop 0
	v_mul_f32_e32 v38, 0x3f317217, v31
	v_fma_f32 v38, v31, s52, -v38
	v_fmac_f32_e32 v38, 0x3377d1cf, v31
	v_fmac_f32_e32 v38, 0x3f317217, v31
	v_mov_b32_e32 v31, v38
	v_add_f32_e32 v38, v70, v34
	v_min_f32_e32 v34, 0, v38
	v_mul_f32_e64 v38, |v38|, s57
	v_exp_f32_e32 v38, v38
	v_pk_add_f32 v[24:25], v[24:25], v[30:31] neg_lo:[0,1] neg_hi:[0,1]
	v_add_f32_e32 v38, 1.0, v38
	v_pk_mul_f32 v[24:25], v[24:25], s[2:3] op_sel_hi:[1,0]
	s_nop 0
	v_log_f32_e32 v38, v38
	s_nop 0
	v_mul_f32_e32 v39, 0x3f317217, v38
	v_fma_f32 v39, v38, s52, -v39
	v_fmac_f32_e32 v39, 0x3377d1cf, v38
	v_fmac_f32_e32 v39, 0x3f317217, v38
	v_mov_b32_e32 v38, v39
	v_add_f32_e32 v39, v66, v26
	v_min_f32_e32 v26, 0, v39
	v_mul_f32_e64 v39, |v39|, s57
	v_exp_f32_e32 v39, v39
	s_nop 0
	v_add_f32_e32 v39, 1.0, v39
	v_log_f32_e32 v39, v39
	s_nop 0
	v_mul_f32_e32 v40, 0x3f317217, v39
	v_fma_f32 v40, v39, s52, -v40
	v_fmac_f32_e32 v40, 0x3377d1cf, v39
	v_fmac_f32_e32 v40, 0x3f317217, v39
	v_mov_b32_e32 v40, v40
	v_add_f32_e32 v39, v71, v35
	v_min_f32_e32 v35, 0, v39
	v_mul_f32_e64 v39, |v39|, s57
	v_exp_f32_e32 v39, v39
	s_nop 0
	v_add_f32_e32 v39, 1.0, v39
	v_log_f32_e32 v39, v39
	s_nop 0
	v_mul_f32_e32 v41, 0x3f317217, v39
	v_fma_f32 v41, v39, s52, -v41
	v_fmac_f32_e32 v41, 0x3377d1cf, v39
	v_fmac_f32_e32 v41, 0x3f317217, v39
	v_mov_b32_e32 v39, v41
	v_pk_add_f32 v[34:35], v[34:35], v[38:39] neg_lo:[0,1] neg_hi:[0,1]
	s_nop 0
	v_pk_mul_f32 v[36:37], v[34:35], s[2:3] op_sel_hi:[1,0]
	v_pk_mul_f32 v[34:35], v[28:29], s[2:3] op_sel_hi:[1,0]
	v_add_f32_e32 v28, v67, v27
	v_min_f32_e32 v27, 0, v28
	v_mul_f32_e64 v28, |v28|, s57
	v_exp_f32_e32 v28, v28
	s_nop 0
	v_add_f32_e32 v28, 1.0, v28
	v_log_f32_e32 v28, v28
	s_nop 0
	v_mul_f32_e32 v29, 0x3f317217, v28
	v_fma_f32 v29, v28, s52, -v29
	v_fmac_f32_e32 v29, 0x3377d1cf, v28
	v_fmac_f32_e32 v29, 0x3f317217, v28
	v_mov_b32_e32 v41, v29
	v_lshlrev_b64 v[28:29], 5, v[32:33]
	v_pk_add_f32 v[26:27], v[26:27], v[40:41] neg_lo:[0,1] neg_hi:[0,1]
	v_lshl_add_u64 v[28:29], s[42:43], 0, v[28:29]
	v_pk_mul_f32 v[26:27], v[26:27], s[2:3] op_sel_hi:[1,0]
	global_store_dwordx4 v[28:29], v[34:37], off
	global_store_dwordx4 v[28:29], v[24:27], off offset:16
	s_nop 1
	v_add_u32_e32 v24, 0x90, v166
	v_ashrrev_i32_e32 v25, 31, v24
	v_lshlrev_b64 v[26:27], 6, v[24:25]
	v_lshl_add_u64 v[38:39], s[82:83], 0, v[26:27]
	flat_load_dwordx4 v[26:29], v[38:39]
	flat_load_dwordx4 v[30:33], v[38:39] offset:16
	flat_load_dwordx4 v[34:37], v[38:39] offset:32
	s_nop 0
	flat_load_dwordx4 v[38:41], v[38:39] offset:48
	s_waitcnt vmcnt(0) lgkmcnt(0)
; __device__ __forceinline__ float logsig_f(float x) { return fminf(x, 0.f) - __logf(1.f + __expf(-fabsf(x))); }
;     __device__ __forceinline__ void operator()(const f32x4 (&acc)[2][2][4][2], const pg8::Unit& u, int wr, int wc, int fr, int fq) const {
;     ...
;                         const int row = row0 + ai * 128 + m * 16;
;                         const f32x4 sv = *(const f32x4*)(ssq + (size_t)row * 16), sv1 = *(const f32x4*)(ssq + (size_t)row * 16 + 4), sv2 = *(const f32x4*)(ssq + (size_t)row * 16 + 8), sv3 = *(const f32x4*)(ssq + (size_t)row * 16 + 12);
;                         const float st = ((sv[0] + sv[1]) + (sv[2] + sv[3])) + ((sv1[0] + sv1[1]) + (sv1[2] + sv1[3])) + ((sv2[0] + sv2[1]) + (sv2[2] + sv2[3])) + ((sv3[0] + sv3[1]) + (sv3[2] + sv3[3]));
;                         const float rs = __builtin_amdgcn_rsqf(st * (1.f / DM) + EPS);
;                         f32x4 a = acc[ai][0][m][0] * rs, b = acc[ai][0][m][1] * rs;
; #pragma unroll
;                         for (int i = 0; i < 4; ++i) { a[i] = logsig_f(a[i] + fb0[i]) * LOG2E; b[i] = logsig_f(b[i] + fb1[i]) * LOG2E; }
;                         *(f32x4*)(FF + (size_t)row * 8) = a; *(f32x4*)(FF + (size_t)row * 8 + 4) = b;
;                         asm volatile("" ::: "memory");
	v_mov_b32_e32 v42, v27
	v_mov_b32_e32 v43, v28
	v_mov_b32_e32 v27, v29
	v_mov_b32_e32 v28, v31
	v_mov_b32_e32 v29, v32
	v_mov_b32_e32 v31, v33
	v_pk_add_f32 v[26:27], v[42:43], v[26:27]
	v_pk_add_f32 v[28:29], v[28:29], v[30:31]
	v_pk_add_f32 v[26:27], v[26:27], v[26:27] op_sel:[0,1] op_sel_hi:[1,0]
	v_pk_add_f32 v[28:29], v[28:29], v[28:29] op_sel:[0,1] op_sel_hi:[1,0]
	v_add_f32_e32 v30, v34, v35
	v_add_f32_e32 v32, v36, v37
	v_mov_b32_e32 v27, v38
	v_mov_b32_e32 v29, v39
	v_mov_b32_e32 v31, v40
	v_mov_b32_e32 v33, v41
	v_pk_add_f32 v[26:27], v[26:27], v[28:29]
	v_pk_add_f32 v[28:29], v[30:31], v[32:33]
	s_nop 0
	v_pk_add_f32 v[26:27], v[26:27], v[28:29]
	s_nop 0
	v_add_f32_e32 v26, v26, v27
	v_fmamk_f32 v26, v26, 0x3a800000, v212
	v_rsq_f32_e32 v28, v26
	s_nop 0
	v_pk_mul_f32 v[20:21], v[20:21], v[28:29] op_sel_hi:[1,0]
	v_pk_mul_f32 v[26:27], v[22:23], v[28:29] op_sel_hi:[1,0]
	v_add_f32_e32 v22, v68, v20
	v_min_f32_e32 v20, 0, v22
	v_mul_f32_e64 v22, |v22|, s57
	v_exp_f32_e32 v22, v22
	v_pk_mul_f32 v[16:17], v[16:17], v[28:29] op_sel_hi:[1,0]
	v_pk_mul_f32 v[18:19], v[18:19], v[28:29] op_sel_hi:[1,0]
	v_add_f32_e32 v22, 1.0, v22
	v_log_f32_e32 v22, v22
	s_nop 0
	v_mul_f32_e32 v23, 0x3f317217, v22
	v_fma_f32 v23, v22, s52, -v23
	v_fmac_f32_e32 v23, 0x3377d1cf, v22
	v_fmac_f32_e32 v23, 0x3f317217, v22
	v_mov_b32_e32 v28, v23
	v_add_f32_e32 v22, v64, v16
	v_min_f32_e32 v16, 0, v22
	v_mul_f32_e64 v22, |v22|, s57
	v_exp_f32_e32 v22, v22
	s_nop 0
	v_add_f32_e32 v22, 1.0, v22
	v_log_f32_e32 v22, v22
	s_nop 0
	v_mul_f32_e32 v23, 0x3f317217, v22
	v_fma_f32 v23, v22, s52, -v23
	v_fmac_f32_e32 v23, 0x3377d1cf, v22
	v_fmac_f32_e32 v23, 0x3f317217, v22
	v_mov_b32_e32 v22, v23
	v_add_f32_e32 v23, v69, v21
	v_min_f32_e32 v21, 0, v23
	v_mul_f32_e64 v23, |v23|, s57
	v_exp_f32_e32 v23, v23
	s_nop 0
	v_add_f32_e32 v23, 1.0, v23
	v_log_f32_e32 v23, v23
	s_nop 0
	v_mul_f32_e32 v29, 0x3f317217, v23
	v_fma_f32 v29, v23, s52, -v29
	v_fmac_f32_e32 v29, 0x3377d1cf, v23
	v_fmac_f32_e32 v29, 0x3f317217, v23
	v_mov_b32_e32 v29, v29
	v_add_f32_e32 v23, v65, v17
	v_min_f32_e32 v17, 0, v23
	v_mul_f32_e64 v23, |v23|, s57
	v_exp_f32_e32 v23, v23
	v_pk_add_f32 v[20:21], v[20:21], v[28:29] neg_lo:[0,1] neg_hi:[0,1]
	v_add_f32_e32 v23, 1.0, v23
	v_log_f32_e32 v23, v23
	s_nop 0
	v_mul_f32_e32 v30, 0x3f317217, v23
	v_fma_f32 v30, v23, s52, -v30
	v_fmac_f32_e32 v30, 0x3377d1cf, v23
	v_fmac_f32_e32 v30, 0x3f317217, v23
	v_mov_b32_e32 v23, v30
	v_add_f32_e32 v30, v70, v26
	v_min_f32_e32 v26, 0, v30
	v_mul_f32_e64 v30, |v30|, s57
	v_exp_f32_e32 v30, v30
	v_pk_add_f32 v[16:17], v[16:17], v[22:23] neg_lo:[0,1] neg_hi:[0,1]
	v_add_f32_e32 v30, 1.0, v30
	v_pk_mul_f32 v[16:17], v[16:17], s[2:3] op_sel_hi:[1,0]
	s_nop 0
	v_log_f32_e32 v30, v30
	s_nop 0
	v_mul_f32_e32 v31, 0x3f317217, v30
	v_fma_f32 v31, v30, s52, -v31
	v_fmac_f32_e32 v31, 0x3377d1cf, v30
	v_fmac_f32_e32 v31, 0x3f317217, v30
	v_mov_b32_e32 v30, v31
	v_add_f32_e32 v31, v66, v18
	v_min_f32_e32 v18, 0, v31
	v_mul_f32_e64 v31, |v31|, s57
	v_exp_f32_e32 v31, v31
	s_nop 0
	v_add_f32_e32 v31, 1.0, v31
	v_log_f32_e32 v31, v31
	s_nop 0
	v_mul_f32_e32 v32, 0x3f317217, v31
	v_fma_f32 v32, v31, s52, -v32
	v_fmac_f32_e32 v32, 0x3377d1cf, v31
	v_fmac_f32_e32 v32, 0x3f317217, v31
	v_mov_b32_e32 v32, v32
	v_add_f32_e32 v31, v71, v27
	v_min_f32_e32 v27, 0, v31
	v_mul_f32_e64 v31, |v31|, s57
	v_exp_f32_e32 v31, v31
	s_nop 0
	v_add_f32_e32 v31, 1.0, v31
	v_log_f32_e32 v31, v31
	s_nop 0
	v_mul_f32_e32 v33, 0x3f317217, v31
	v_fma_f32 v33, v31, s52, -v33
	v_fmac_f32_e32 v33, 0x3377d1cf, v31
	v_fmac_f32_e32 v33, 0x3f317217, v31
	v_mov_b32_e32 v31, v33
	v_pk_add_f32 v[26:27], v[26:27], v[30:31] neg_lo:[0,1] neg_hi:[0,1]
	s_nop 0
	v_pk_mul_f32 v[28:29], v[26:27], s[2:3] op_sel_hi:[1,0]
	v_pk_mul_f32 v[26:27], v[20:21], s[2:3] op_sel_hi:[1,0]
	v_add_f32_e32 v20, v67, v19
	v_min_f32_e32 v19, 0, v20
	v_mul_f32_e64 v20, |v20|, s57
	v_exp_f32_e32 v20, v20
	s_nop 0
	v_add_f32_e32 v20, 1.0, v20
	v_log_f32_e32 v20, v20
	s_nop 0
	v_mul_f32_e32 v21, 0x3f317217, v20
	v_fma_f32 v21, v20, s52, -v21
	v_fmac_f32_e32 v21, 0x3377d1cf, v20
	v_fmac_f32_e32 v21, 0x3f317217, v20
	v_mov_b32_e32 v33, v21
	v_lshlrev_b64 v[20:21], 5, v[24:25]
	v_pk_add_f32 v[18:19], v[18:19], v[32:33] neg_lo:[0,1] neg_hi:[0,1]
	v_lshl_add_u64 v[20:21], s[42:43], 0, v[20:21]
	v_pk_mul_f32 v[18:19], v[18:19], s[2:3] op_sel_hi:[1,0]
	global_store_dwordx4 v[20:21], v[26:29], off
	global_store_dwordx4 v[20:21], v[16:19], off offset:16
	s_nop 1
	v_add_u32_e32 v16, 0xa0, v166
	v_ashrrev_i32_e32 v17, 31, v16
	v_lshlrev_b64 v[18:19], 6, v[16:17]
	v_lshl_add_u64 v[30:31], s[82:83], 0, v[18:19]
	flat_load_dwordx4 v[18:21], v[30:31]
	flat_load_dwordx4 v[22:25], v[30:31] offset:16
	flat_load_dwordx4 v[26:29], v[30:31] offset:32
	s_nop 0
	flat_load_dwordx4 v[30:33], v[30:31] offset:48
	s_waitcnt vmcnt(0) lgkmcnt(0)
; __device__ __forceinline__ float logsig_f(float x) { return fminf(x, 0.f) - __logf(1.f + __expf(-fabsf(x))); }
;     __device__ __forceinline__ void operator()(const f32x4 (&acc)[2][2][4][2], const pg8::Unit& u, int wr, int wc, int fr, int fq) const {
;     ...
;                         const int row = row0 + ai * 128 + m * 16;
;                         const f32x4 sv = *(const f32x4*)(ssq + (size_t)row * 16), sv1 = *(const f32x4*)(ssq + (size_t)row * 16 + 4), sv2 = *(const f32x4*)(ssq + (size_t)row * 16 + 8), sv3 = *(const f32x4*)(ssq + (size_t)row * 16 + 12);
;                         const float st = ((sv[0] + sv[1]) + (sv[2] + sv[3])) + ((sv1[0] + sv1[1]) + (sv1[2] + sv1[3])) + ((sv2[0] + sv2[1]) + (sv2[2] + sv2[3])) + ((sv3[0] + sv3[1]) + (sv3[2] + sv3[3]));
;                         const float rs = __builtin_amdgcn_rsqf(st * (1.f / DM) + EPS);
;                         f32x4 a = acc[ai][0][m][0] * rs, b = acc[ai][0][m][1] * rs;
; #pragma unroll
;                         for (int i = 0; i < 4; ++i) { a[i] = logsig_f(a[i] + fb0[i]) * LOG2E; b[i] = logsig_f(b[i] + fb1[i]) * LOG2E; }
;                         *(f32x4*)(FF + (size_t)row * 8) = a; *(f32x4*)(FF + (size_t)row * 8 + 4) = b;
;                         asm volatile("" ::: "memory");
	v_mov_b32_e32 v34, v19
	v_mov_b32_e32 v35, v20
	v_mov_b32_e32 v19, v21
	v_mov_b32_e32 v20, v23
	v_mov_b32_e32 v21, v24
	v_mov_b32_e32 v23, v25
	v_pk_add_f32 v[18:19], v[34:35], v[18:19]
	v_pk_add_f32 v[20:21], v[20:21], v[22:23]
	v_pk_add_f32 v[18:19], v[18:19], v[18:19] op_sel:[0,1] op_sel_hi:[1,0]
	v_pk_add_f32 v[20:21], v[20:21], v[20:21] op_sel:[0,1] op_sel_hi:[1,0]
	v_add_f32_e32 v22, v26, v27
	v_add_f32_e32 v24, v28, v29
	v_mov_b32_e32 v19, v30
	v_mov_b32_e32 v21, v31
	v_mov_b32_e32 v23, v32
	v_mov_b32_e32 v25, v33
	v_pk_add_f32 v[18:19], v[18:19], v[20:21]
	v_pk_add_f32 v[20:21], v[22:23], v[24:25]
	s_nop 0
	v_pk_add_f32 v[18:19], v[18:19], v[20:21]
	s_nop 0
	v_add_f32_e32 v18, v18, v19
	v_fmamk_f32 v18, v18, 0x3a800000, v212
	v_rsq_f32_e32 v20, v18
	s_nop 0
	v_pk_mul_f32 v[12:13], v[12:13], v[20:21] op_sel_hi:[1,0]
	v_pk_mul_f32 v[18:19], v[14:15], v[20:21] op_sel_hi:[1,0]
	v_add_f32_e32 v14, v68, v12
	v_min_f32_e32 v12, 0, v14
	v_mul_f32_e64 v14, |v14|, s57
	v_exp_f32_e32 v14, v14
	v_pk_mul_f32 v[8:9], v[8:9], v[20:21] op_sel_hi:[1,0]
	v_pk_mul_f32 v[10:11], v[10:11], v[20:21] op_sel_hi:[1,0]
	v_add_f32_e32 v14, 1.0, v14
	v_log_f32_e32 v14, v14
	s_nop 0
	v_mul_f32_e32 v15, 0x3f317217, v14
	v_fma_f32 v15, v14, s52, -v15
	v_fmac_f32_e32 v15, 0x3377d1cf, v14
	v_fmac_f32_e32 v15, 0x3f317217, v14
	v_mov_b32_e32 v20, v15
	v_add_f32_e32 v14, v64, v8
	v_min_f32_e32 v8, 0, v14
	v_mul_f32_e64 v14, |v14|, s57
	v_exp_f32_e32 v14, v14
	s_nop 0
	v_add_f32_e32 v14, 1.0, v14
	v_log_f32_e32 v14, v14
	s_nop 0
	v_mul_f32_e32 v15, 0x3f317217, v14
	v_fma_f32 v15, v14, s52, -v15
	v_fmac_f32_e32 v15, 0x3377d1cf, v14
	v_fmac_f32_e32 v15, 0x3f317217, v14
	v_mov_b32_e32 v14, v15
	v_add_f32_e32 v15, v69, v13
	v_min_f32_e32 v13, 0, v15
	v_mul_f32_e64 v15, |v15|, s57
	v_exp_f32_e32 v15, v15
	s_nop 0
	v_add_f32_e32 v15, 1.0, v15
	v_log_f32_e32 v15, v15
	s_nop 0
	v_mul_f32_e32 v21, 0x3f317217, v15
	v_fma_f32 v21, v15, s52, -v21
	v_fmac_f32_e32 v21, 0x3377d1cf, v15
	v_fmac_f32_e32 v21, 0x3f317217, v15
	v_mov_b32_e32 v21, v21
	v_add_f32_e32 v15, v65, v9
	v_min_f32_e32 v9, 0, v15
	v_mul_f32_e64 v15, |v15|, s57
	v_exp_f32_e32 v15, v15
	v_pk_add_f32 v[12:13], v[12:13], v[20:21] neg_lo:[0,1] neg_hi:[0,1]
	v_add_f32_e32 v15, 1.0, v15
	v_log_f32_e32 v15, v15
	s_nop 0
	v_mul_f32_e32 v22, 0x3f317217, v15
	v_fma_f32 v22, v15, s52, -v22
	v_fmac_f32_e32 v22, 0x3377d1cf, v15
	v_fmac_f32_e32 v22, 0x3f317217, v15
	v_mov_b32_e32 v15, v22
	v_add_f32_e32 v22, v70, v18
	v_min_f32_e32 v18, 0, v22
	v_mul_f32_e64 v22, |v22|, s57
	v_exp_f32_e32 v22, v22
	v_pk_add_f32 v[8:9], v[8:9], v[14:15] neg_lo:[0,1] neg_hi:[0,1]
	v_add_f32_e32 v22, 1.0, v22
	v_pk_mul_f32 v[8:9], v[8:9], s[2:3] op_sel_hi:[1,0]
	s_nop 0
	v_log_f32_e32 v22, v22
	s_nop 0
	v_mul_f32_e32 v23, 0x3f317217, v22
	v_fma_f32 v23, v22, s52, -v23
	v_fmac_f32_e32 v23, 0x3377d1cf, v22
	v_fmac_f32_e32 v23, 0x3f317217, v22
	v_mov_b32_e32 v22, v23
	v_add_f32_e32 v23, v66, v10
	v_min_f32_e32 v10, 0, v23
	v_mul_f32_e64 v23, |v23|, s57
	v_exp_f32_e32 v23, v23
	s_nop 0
	v_add_f32_e32 v23, 1.0, v23
	v_log_f32_e32 v23, v23
	s_nop 0
	v_mul_f32_e32 v24, 0x3f317217, v23
	v_fma_f32 v24, v23, s52, -v24
	v_fmac_f32_e32 v24, 0x3377d1cf, v23
	v_fmac_f32_e32 v24, 0x3f317217, v23
	v_mov_b32_e32 v24, v24
	v_add_f32_e32 v23, v71, v19
	v_min_f32_e32 v19, 0, v23
	v_mul_f32_e64 v23, |v23|, s57
	v_exp_f32_e32 v23, v23
	s_nop 0
	v_add_f32_e32 v23, 1.0, v23
	v_log_f32_e32 v23, v23
	s_nop 0
	v_mul_f32_e32 v25, 0x3f317217, v23
	v_fma_f32 v25, v23, s52, -v25
	v_fmac_f32_e32 v25, 0x3377d1cf, v23
	v_fmac_f32_e32 v25, 0x3f317217, v23
	v_mov_b32_e32 v23, v25
	v_pk_add_f32 v[18:19], v[18:19], v[22:23] neg_lo:[0,1] neg_hi:[0,1]
	s_nop 0
	v_pk_mul_f32 v[20:21], v[18:19], s[2:3] op_sel_hi:[1,0]
	v_pk_mul_f32 v[18:19], v[12:13], s[2:3] op_sel_hi:[1,0]
	v_add_f32_e32 v12, v67, v11
	v_min_f32_e32 v11, 0, v12
	v_mul_f32_e64 v12, |v12|, s57
	v_exp_f32_e32 v12, v12
	s_nop 0
	v_add_f32_e32 v12, 1.0, v12
	v_log_f32_e32 v12, v12
	s_nop 0
	v_mul_f32_e32 v13, 0x3f317217, v12
	v_fma_f32 v13, v12, s52, -v13
	v_fmac_f32_e32 v13, 0x3377d1cf, v12
	v_fmac_f32_e32 v13, 0x3f317217, v12
	v_mov_b32_e32 v25, v13
	v_lshlrev_b64 v[12:13], 5, v[16:17]
	v_pk_add_f32 v[10:11], v[10:11], v[24:25] neg_lo:[0,1] neg_hi:[0,1]
	v_lshl_add_u64 v[12:13], s[42:43], 0, v[12:13]
	v_pk_mul_f32 v[10:11], v[10:11], s[2:3] op_sel_hi:[1,0]
	global_store_dwordx4 v[12:13], v[18:21], off
	global_store_dwordx4 v[12:13], v[8:11], off offset:16
	s_nop 1
	v_add_u32_e32 v8, 0xb0, v166
	v_ashrrev_i32_e32 v9, 31, v8
	v_lshlrev_b64 v[10:11], 6, v[8:9]
	v_lshl_add_u64 v[22:23], s[82:83], 0, v[10:11]
	flat_load_dwordx4 v[10:13], v[22:23]
	flat_load_dwordx4 v[14:17], v[22:23] offset:16
	flat_load_dwordx4 v[18:21], v[22:23] offset:32
	s_nop 0
	flat_load_dwordx4 v[22:25], v[22:23] offset:48
	s_waitcnt vmcnt(0) lgkmcnt(0)
; __device__ __forceinline__ float logsig_f(float x) { return fminf(x, 0.f) - __logf(1.f + __expf(-fabsf(x))); }
;     __device__ __forceinline__ void operator()(const f32x4 (&acc)[2][2][4][2], const pg8::Unit& u, int wr, int wc, int fr, int fq) const {
;     ...
;                         const int row = row0 + ai * 128 + m * 16;
;                         const f32x4 sv = *(const f32x4*)(ssq + (size_t)row * 16), sv1 = *(const f32x4*)(ssq + (size_t)row * 16 + 4), sv2 = *(const f32x4*)(ssq + (size_t)row * 16 + 8), sv3 = *(const f32x4*)(ssq + (size_t)row * 16 + 12);
;                         const float st = ((sv[0] + sv[1]) + (sv[2] + sv[3])) + ((sv1[0] + sv1[1]) + (sv1[2] + sv1[3])) + ((sv2[0] + sv2[1]) + (sv2[2] + sv2[3])) + ((sv3[0] + sv3[1]) + (sv3[2] + sv3[3]));
;                         const float rs = __builtin_amdgcn_rsqf(st * (1.f / DM) + EPS);
;                         f32x4 a = acc[ai][0][m][0] * rs, b = acc[ai][0][m][1] * rs;
; #pragma unroll
;                         for (int i = 0; i < 4; ++i) { a[i] = logsig_f(a[i] + fb0[i]) * LOG2E; b[i] = logsig_f(b[i] + fb1[i]) * LOG2E; }
;                         *(f32x4*)(FF + (size_t)row * 8) = a; *(f32x4*)(FF + (size_t)row * 8 + 4) = b;
;                         asm volatile("" ::: "memory");
	v_mov_b32_e32 v26, v11
	v_mov_b32_e32 v27, v12
	v_mov_b32_e32 v11, v13
	v_mov_b32_e32 v12, v15
	v_mov_b32_e32 v13, v16
	v_mov_b32_e32 v15, v17
	v_pk_add_f32 v[10:11], v[26:27], v[10:11]
	v_pk_add_f32 v[12:13], v[12:13], v[14:15]
	v_pk_add_f32 v[10:11], v[10:11], v[10:11] op_sel:[0,1] op_sel_hi:[1,0]
	v_pk_add_f32 v[12:13], v[12:13], v[12:13] op_sel:[0,1] op_sel_hi:[1,0]
	v_add_f32_e32 v14, v18, v19
	v_add_f32_e32 v16, v20, v21
	v_mov_b32_e32 v11, v22
	v_mov_b32_e32 v13, v23
	v_mov_b32_e32 v15, v24
	v_mov_b32_e32 v17, v25
	v_pk_add_f32 v[10:11], v[10:11], v[12:13]
	v_pk_add_f32 v[12:13], v[14:15], v[16:17]
	s_nop 0
	v_pk_add_f32 v[10:11], v[10:11], v[12:13]
	s_nop 0
	v_add_f32_e32 v10, v10, v11
	v_fmamk_f32 v10, v10, 0x3a800000, v212
	v_rsq_f32_e32 v12, v10
	s_nop 0
	v_pk_mul_f32 v[4:5], v[4:5], v[12:13] op_sel_hi:[1,0]
	v_pk_mul_f32 v[10:11], v[6:7], v[12:13] op_sel_hi:[1,0]
	v_add_f32_e32 v6, v68, v4
	v_min_f32_e32 v4, 0, v6
	v_mul_f32_e64 v6, |v6|, s57
	v_exp_f32_e32 v6, v6
	v_pk_mul_f32 v[0:1], v[0:1], v[12:13] op_sel_hi:[1,0]
	v_pk_mul_f32 v[2:3], v[2:3], v[12:13] op_sel_hi:[1,0]
	v_add_f32_e32 v6, 1.0, v6
	v_log_f32_e32 v6, v6
	s_nop 0
	v_mul_f32_e32 v7, 0x3f317217, v6
	v_fma_f32 v7, v6, s52, -v7
	v_fmac_f32_e32 v7, 0x3377d1cf, v6
	v_fmac_f32_e32 v7, 0x3f317217, v6
	v_mov_b32_e32 v12, v7
	v_add_f32_e32 v6, v64, v0
	v_min_f32_e32 v0, 0, v6
	v_mul_f32_e64 v6, |v6|, s57
	v_exp_f32_e32 v6, v6
	s_nop 0
	v_add_f32_e32 v6, 1.0, v6
	v_log_f32_e32 v6, v6
	s_nop 0
	v_mul_f32_e32 v7, 0x3f317217, v6
	v_fma_f32 v7, v6, s52, -v7
	v_fmac_f32_e32 v7, 0x3377d1cf, v6
	v_fmac_f32_e32 v7, 0x3f317217, v6
	v_mov_b32_e32 v6, v7
	v_add_f32_e32 v7, v69, v5
	v_min_f32_e32 v5, 0, v7
	v_mul_f32_e64 v7, |v7|, s57
	v_exp_f32_e32 v7, v7
	s_nop 0
	v_add_f32_e32 v7, 1.0, v7
	v_log_f32_e32 v7, v7
	s_nop 0
	v_mul_f32_e32 v13, 0x3f317217, v7
	v_fma_f32 v13, v7, s52, -v13
	v_fmac_f32_e32 v13, 0x3377d1cf, v7
	v_fmac_f32_e32 v13, 0x3f317217, v7
	v_mov_b32_e32 v13, v13
	v_add_f32_e32 v7, v65, v1
	v_min_f32_e32 v1, 0, v7
	v_mul_f32_e64 v7, |v7|, s57
	v_exp_f32_e32 v7, v7
	v_pk_add_f32 v[4:5], v[4:5], v[12:13] neg_lo:[0,1] neg_hi:[0,1]
	v_add_f32_e32 v7, 1.0, v7
	v_log_f32_e32 v7, v7
	s_nop 0
	v_mul_f32_e32 v14, 0x3f317217, v7
	v_fma_f32 v14, v7, s52, -v14
	v_fmac_f32_e32 v14, 0x3377d1cf, v7
	v_fmac_f32_e32 v14, 0x3f317217, v7
	v_mov_b32_e32 v7, v14
	v_add_f32_e32 v14, v70, v10
	v_min_f32_e32 v10, 0, v14
	v_mul_f32_e64 v14, |v14|, s57
	v_exp_f32_e32 v14, v14
	v_pk_add_f32 v[0:1], v[0:1], v[6:7] neg_lo:[0,1] neg_hi:[0,1]
	v_add_f32_e32 v14, 1.0, v14
	v_pk_mul_f32 v[0:1], v[0:1], s[2:3] op_sel_hi:[1,0]
	s_nop 0
	v_log_f32_e32 v14, v14
	s_nop 0
	v_mul_f32_e32 v15, 0x3f317217, v14
	v_fma_f32 v15, v14, s52, -v15
	v_fmac_f32_e32 v15, 0x3377d1cf, v14
	v_fmac_f32_e32 v15, 0x3f317217, v14
	v_mov_b32_e32 v14, v15
	v_add_f32_e32 v15, v66, v2
	v_min_f32_e32 v2, 0, v15
	v_mul_f32_e64 v15, |v15|, s57
	v_exp_f32_e32 v15, v15
	s_nop 0
	v_add_f32_e32 v15, 1.0, v15
	v_log_f32_e32 v15, v15
	s_nop 0
	v_mul_f32_e32 v16, 0x3f317217, v15
	v_fma_f32 v16, v15, s52, -v16
	v_fmac_f32_e32 v16, 0x3377d1cf, v15
	v_fmac_f32_e32 v16, 0x3f317217, v15
	v_mov_b32_e32 v16, v16
	v_add_f32_e32 v15, v71, v11
	v_min_f32_e32 v11, 0, v15
	v_mul_f32_e64 v15, |v15|, s57
	v_exp_f32_e32 v15, v15
	s_nop 0
	v_add_f32_e32 v15, 1.0, v15
	v_log_f32_e32 v15, v15
	s_nop 0
	v_mul_f32_e32 v17, 0x3f317217, v15
	v_fma_f32 v17, v15, s52, -v17
	v_fmac_f32_e32 v17, 0x3377d1cf, v15
	v_fmac_f32_e32 v17, 0x3f317217, v15
	v_mov_b32_e32 v15, v17
	v_pk_add_f32 v[10:11], v[10:11], v[14:15] neg_lo:[0,1] neg_hi:[0,1]
	s_nop 0
	v_pk_mul_f32 v[12:13], v[10:11], s[2:3] op_sel_hi:[1,0]
	v_pk_mul_f32 v[10:11], v[4:5], s[2:3] op_sel_hi:[1,0]
	v_add_f32_e32 v4, v67, v3
	v_min_f32_e32 v3, 0, v4
	v_mul_f32_e64 v4, |v4|, s57
	v_exp_f32_e32 v4, v4
	s_nop 0
	v_add_f32_e32 v4, 1.0, v4
	v_log_f32_e32 v4, v4
	s_nop 0
	v_mul_f32_e32 v5, 0x3f317217, v4
	v_fma_f32 v5, v4, s52, -v5
	v_fmac_f32_e32 v5, 0x3377d1cf, v4
	v_fmac_f32_e32 v5, 0x3f317217, v4
	v_mov_b32_e32 v17, v5
	v_lshlrev_b64 v[4:5], 5, v[8:9]
	v_pk_add_f32 v[2:3], v[2:3], v[16:17] neg_lo:[0,1] neg_hi:[0,1]
	v_lshl_add_u64 v[4:5], s[42:43], 0, v[4:5]
	v_pk_mul_f32 v[2:3], v[2:3], s[2:3] op_sel_hi:[1,0]
	global_store_dwordx4 v[4:5], v[10:13], off
	global_store_dwordx4 v[4:5], v[0:3], off offset:16
